# seam-0 barrier: per-XCD arrival words; only the last workgroup of an XCD writes its L2 back and reports the XCD census count to the polled word
# speedup vs baseline: 1.0327x; 1.0327x over previous
; #define LAS __attribute__((address_space(3)))
; __device__ __forceinline__ unsigned xb_add(unsigned* p, unsigned v) { return __hip_atomic_fetch_add(p, v, __ATOMIC_RELAXED, __HIP_MEMORY_SCOPE_AGENT); }
; __device__ __forceinline__ unsigned xb_xcc_id() { return (unsigned)__builtin_amdgcn_s_getreg((3 << 11) | 20) & 0xFu; }
; __device__ __forceinline__ XcdBarrier xcd_barrier_post(unsigned* bar, volatile LAS unsigned* st) {
;     XcdBarrier b; b.bar = bar; b.x = xb_xcc_id(); b.st = st;
;     if (threadIdx.x == 0) (void)xb_add(&bar[XB_XCNT(b.x)], 1u);
;     return b;
; }
.LBB0_49:
	s_or_b64 exec, exec, s[0:1]
	v_lshrrev_b32_e32 v1, 20, v0
	v_lshrrev_b32_e32 v0, 10, v0
	v_or_b32_e32 v0, v0, v1
	s_movk_i32 s0, 0x3ff
	v_and_or_b32 v0, v0, s0, v178
	v_cmp_eq_u32_e32 vcc, 0, v0
	s_waitcnt vmcnt(0)
	s_barrier
	s_and_saveexec_b64 s[0:1], vcc
	s_cbranch_execz .LBB0_59
	s_lshl_b32 s4, s34, 7
	s_lshl_b32 s5, s34, 8
	s_add_i32 s4, s4, 0x3600
	v_mov_b32_e32 v2, s4
	v_mov_b32_e32 v3, 1
	v_mov_b32_e32 v6, s5
	global_atomic_add v4, v2, v3, s[26:27] sc0
	global_load_dword v5, v6, s[26:27] offset:1024 sc1
	s_waitcnt vmcnt(0)
	v_add_u32_e32 v4, 1, v4
	v_mov_b32_e32 v2, 0
	v_cmp_eq_u32_e32 vcc, v4, v5
	s_and_saveexec_b64 s[8:9], vcc
	s_cbranch_execz .Lsync0_notlast
	buffer_wbl2 sc1
	s_waitcnt vmcnt(0)
	global_atomic_add v2, v5, s[26:27] offset:256
.Lsync0_notlast:
	s_or_b64 exec, exec, s[8:9]
	s_mov_b64 s[8:9], exec
	s_mov_b64 s[6:7], 0
	s_mov_b32 s4, 0
